# TD1: team-barrier wait deferred into the next GEMM phase prologue, after the weight-tile LDS-DMA loads are issued (phase setup and weight loads overlap the wait), on top of v074
# baseline (speedup 1.0000x reference)
.LBB0_5:
	s_or_b64 exec, exec, s[0:1]
	s_add_u32 s24, s96, 0xea80000
	s_addc_u32 s25, s97, 0
	s_add_u32 s28, s96, 0x6080000
	s_addc_u32 s29, s97, 0
	s_add_u32 s20, s96, 0x8080000
	s_addc_u32 s35, s97, 0
	s_add_u32 s6, s96, 0x4200000
	s_addc_u32 s7, s97, 0
	v_writelane_b32 v250, s6, 50
	s_cmpk_lt_i32 s69, 0x200
	v_lshrrev_b32_e32 v1, 20, v0
	v_writelane_b32 v250, s7, 51
	s_cselect_b64 s[6:7], -1, 0
	v_writelane_b32 v250, s6, 52
	s_cmpk_eq_i32 s98, 0x100
	v_lshrrev_b32_e32 v0, 10, v0
	v_writelane_b32 v250, s7, 53
	s_cselect_b64 s[6:7], -1, 0
	v_writelane_b32 v250, s6, 54
	s_and_b32 s1, s69, 7
	s_lshr_b32 s86, s69, 3
	v_writelane_b32 v250, s7, 55
	s_ashr_i32 s6, s69, 3
	s_and_b32 s6, s6, -8
	s_or_b32 s87, s6, s1
	s_cmp_lg_u32 0, -1
	s_cselect_b64 s[30:31], -1, 0
	s_lshl_b32 s16, s69, 3
	s_lshl_b32 s83, s98, 3
	s_add_u32 s6, s96, 0x4e00000
	s_addc_u32 s7, s97, 0
	v_writelane_b32 v250, s6, 56
	s_ashr_i32 s1, s69, 31
	s_and_b32 s9, s29, 0xffff
	v_writelane_b32 v250, s7, 57
	v_writelane_b32 v250, s1, 58
	s_lshr_b32 s1, s1, 29
	s_add_i32 s1, s69, s1
	s_ashr_i32 s6, s1, 3
	s_and_b32 s1, s1, -8
	v_writelane_b32 v250, s6, 59
	s_sub_i32 s6, s69, s1
	s_ashr_i32 s1, s98, 31
	s_add_u32 s10, s96, 0xe280000
	v_writelane_b32 v250, s1, 60
	s_addc_u32 s11, s97, 0
	v_writelane_b32 v250, s10, 61
	s_mul_i32 s0, s99, s98
	v_or_b32_e32 v0, v0, v1
	v_writelane_b32 v250, s11, 62
	s_add_u32 s10, s96, 0xeb15100
	s_addc_u32 s11, s97, 0
	v_writelane_b32 v250, s10, 63
	s_mul_i32 s90, s0, s8
	v_readlane_b32 s36, v250, 2
	v_writelane_b32 v249, s11, 0
	s_add_u32 s10, s96, 0xeb11000
	s_addc_u32 s11, s97, 0
	s_not_b32 s1, s69
	v_writelane_b32 v249, s10, 1
	s_add_i32 s1, s98, s1
	s_cmp_lt_i32 s1, 64
	v_writelane_b32 v249, s11, 2
	v_writelane_b32 v249, s1, 3
	s_cselect_b64 s[10:11], -1, 0
	v_writelane_b32 v249, s10, 4
	s_movk_i32 s1, 0x3ff
	v_and_or_b32 v1, v0, s1, v220
	v_writelane_b32 v249, s11, 5
	s_add_u32 s10, s96, 0x4600000
	s_addc_u32 s11, s97, 0
	v_writelane_b32 v249, s10, 6
	v_readlane_b32 s46, v250, 12
	v_readlane_b32 s47, v250, 13
	v_writelane_b32 v249, s11, 7
	s_add_u32 s10, s96, 0xeb10000
	s_addc_u32 s11, s97, 0
	s_add_u32 s68, s96, 0xe680000
	s_addc_u32 s80, s97, 0
	s_lshl_b32 s91, s69, 9
	s_lshl_b32 s81, s98, 9
	v_writelane_b32 v249, s10, 8
	s_cmp_eq_u32 s69, 0
	s_cselect_b64 s[0:1], -1, 0
	v_writelane_b32 v249, s11, 9
	v_writelane_b32 v249, s0, 10
	s_cmpk_lt_i32 s69, 0x20a0
	s_mov_b32 s8, s28
	v_writelane_b32 v249, s1, 11
	s_cselect_b64 s[0:1], -1, 0
	v_writelane_b32 v249, s0, 12
	s_brev_b32 s10, 64
	v_cmp_eq_u32_e64 s[22:23], 0, v1
	v_writelane_b32 v249, s1, 13
	s_add_u32 s0, s96, 0xe080000
	s_addc_u32 s1, s97, 0
	s_add_u32 s70, s96, 0x5880000
	v_writelane_b32 v249, s0, 14
	s_addc_u32 s71, s97, 0
	s_mov_b32 s34, s20
	v_writelane_b32 v249, s1, 15
	s_add_u32 s0, s46, 0x1000
	s_addc_u32 s1, s47, 0
	v_writelane_b32 v249, s0, 16
	v_readlane_b32 s37, v250, 3
	s_mov_b32 s12, 0x41980000
	v_writelane_b32 v249, s1, 17
	s_add_u32 s0, s96, 0x5680000
	s_addc_u32 s1, s97, 0
	v_writelane_b32 v249, s0, 18
	s_mov_b32 s14, 0x41c80000
	v_mbcnt_lo_u32_b32 v227, -1, 0
	v_writelane_b32 v249, s1, 19
	s_add_u32 s0, s96, 0x5200000
	s_addc_u32 s1, s97, 0
	v_writelane_b32 v249, s0, 20
	v_mov_b32_e32 v0, 0
	s_mov_b32 s13, 0x41c00000
	v_writelane_b32 v249, s1, 21
	s_add_u32 s0, s96, 0x5e80000
	s_addc_u32 s1, s97, 0
	v_writelane_b32 v249, s0, 22
	s_mov_b32 s15, 0x41d00000
	v_mov_b32_e32 v221, 0x358637bd
	v_writelane_b32 v249, s1, 23
	s_add_u32 s0, s96, 0x3700000
	s_addc_u32 s1, s97, 0
	v_writelane_b32 v249, s0, 24
	v_mov_b32_e32 v222, 1
	v_mov_b32_e32 v223, 0x42800000
	v_writelane_b32 v249, s1, 25
	s_add_u32 s0, s96, 0x2100000
	s_addc_u32 s1, s97, 0
	v_writelane_b32 v249, s0, 26
	v_mov_b32_e32 v224, 0xfff
	v_mov_b32_e32 v225, 0x1800
	v_writelane_b32 v249, s1, 27
	s_add_u32 s0, s96, 0x1600000
	s_addc_u32 s1, s97, 0
	v_writelane_b32 v249, s0, 28
	s_cmp_eq_u64 s[96:97], 0
	v_mov_b32_e32 v226, 0xff800000
	v_writelane_b32 v249, s1, 29
	s_cselect_b64 s[0:1], -1, 0
	v_writelane_b32 v249, s0, 30
	v_mbcnt_hi_u32_b32 v228, -1, v227
	v_not_b32_e32 v229, 63
	v_writelane_b32 v249, s1, 31
	s_add_u32 s0, s96, 0xeb11300
	s_addc_u32 s1, s97, 0
	v_writelane_b32 v249, s0, 32
	v_mov_b32_e32 v230, 0xffffd0c0
	v_mov_b32_e32 v231, 0xffffd3c0
	v_writelane_b32 v249, s1, 33
	s_add_u32 s0, s96, 0xeb11500
	s_addc_u32 s1, s97, 0
	v_writelane_b32 v249, s0, 34
	v_mov_b32_e32 v232, 0xffffd4c0
	s_movk_i32 s89, 0x1800
	v_writelane_b32 v249, s1, 35
	s_add_u32 s0, s96, 0xeb11600
	s_addc_u32 s1, s97, 0
	v_writelane_b32 v249, s0, 36
	s_movk_i32 s19, 0x1200
	s_mov_b32 s17, 0
	v_writelane_b32 v249, s1, 37
	s_add_u32 s0, s96, 0xeb11700
	s_addc_u32 s1, s97, 0
	v_writelane_b32 v249, s0, 38
	s_mov_b32 s18, 0x3e38aa3b
	s_mov_b64 s[36:37], 0x80
	v_writelane_b32 v249, s1, 39
	s_add_u32 s0, s96, 0xeb11800
	s_addc_u32 s1, s97, 0
	v_writelane_b32 v249, s0, 40
	s_mov_b64 s[26:27], 0x400c0
	v_readlane_b32 s38, v250, 4
	v_writelane_b32 v249, s1, 41
	s_add_u32 s0, s96, 0xeb11900
	s_addc_u32 s1, s97, 0
	v_writelane_b32 v249, s0, 42
	v_readlane_b32 s39, v250, 5
	v_readlane_b32 s40, v250, 6
	v_writelane_b32 v249, s1, 43
	s_add_u32 s0, s96, 0xeb11a00
	s_addc_u32 s1, s97, 0
	v_writelane_b32 v249, s0, 44
	v_readlane_b32 s41, v250, 7
	v_readlane_b32 s42, v250, 8
	v_writelane_b32 v249, s1, 45
	s_add_u32 s0, s96, 0xeb11b00
	s_addc_u32 s1, s97, 0
	v_writelane_b32 v249, s0, 46
	v_readlane_b32 s43, v250, 9
	v_readlane_b32 s44, v250, 10
	v_writelane_b32 v249, s1, 47
	s_add_u32 s0, s96, 0xeb11c00
	s_addc_u32 s1, s97, 0
	v_writelane_b32 v249, s0, 48
	v_readlane_b32 s45, v250, 11
	v_readlane_b32 s48, v250, 14
	v_writelane_b32 v249, s1, 49
	s_add_u32 s0, s96, 0xeb11d00
	s_addc_u32 s1, s97, 0
	v_writelane_b32 v249, s0, 50
	v_readlane_b32 s49, v250, 15
	v_readlane_b32 s50, v250, 16
	v_writelane_b32 v249, s1, 51
	s_add_u32 s0, s96, 0xeb11e00
	s_addc_u32 s1, s97, 0
	v_writelane_b32 v249, s0, 52
	v_readlane_b32 s51, v250, 17
	s_nop 0
	v_writelane_b32 v249, s1, 53
	s_add_u32 s0, s96, 0xeb11f00
	s_addc_u32 s1, s97, 0
	v_writelane_b32 v249, s0, 54
	s_nop 1
	v_writelane_b32 v249, s1, 55
	s_add_u32 s0, s96, 0xeb12000
	s_addc_u32 s1, s97, 0
	v_writelane_b32 v249, s0, 56
	s_nop 1
	v_writelane_b32 v249, s1, 57
	s_add_u32 s0, s96, 0xeb12100
	s_addc_u32 s1, s97, 0
	v_writelane_b32 v249, s0, 58
	s_nop 1
	v_writelane_b32 v249, s1, 59
	s_add_u32 s0, s96, 0xeb12200
	s_addc_u32 s1, s97, 0
	v_writelane_b32 v249, s0, 60
	s_nop 1
	v_writelane_b32 v249, s1, 61
	s_add_u32 s0, s96, 0xeb12300
	s_addc_u32 s1, s97, 0
	v_writelane_b32 v249, s0, 62
	s_nop 1
	v_writelane_b32 v249, s1, 63
	s_add_u32 s0, s96, 0xeb12400
	s_addc_u32 s1, s97, 0
	v_writelane_b32 v248, s0, 0
	s_cmp_eq_u32 s3, 15
	s_nop 0
	v_writelane_b32 v248, s1, 1
	s_cselect_b64 s[0:1], -1, 0
	v_writelane_b32 v248, s0, 2
	s_cmp_eq_u32 s3, 14
	s_nop 0
	v_writelane_b32 v248, s1, 3
	s_cselect_b64 s[0:1], -1, 0
	v_writelane_b32 v248, s0, 4
	s_cmp_eq_u32 s3, 13
	s_nop 0
	v_writelane_b32 v248, s1, 5
	s_cselect_b64 s[0:1], -1, 0
	v_writelane_b32 v248, s0, 6
	s_cmp_eq_u32 s3, 12
	s_nop 0
	v_writelane_b32 v248, s1, 7
	s_cselect_b64 s[0:1], -1, 0
	v_writelane_b32 v248, s0, 8
	s_cmp_eq_u32 s3, 11
	s_nop 0
	v_writelane_b32 v248, s1, 9
	s_cselect_b64 s[0:1], -1, 0
	v_writelane_b32 v248, s0, 10
	s_cmp_eq_u32 s3, 10
	s_nop 0
	v_writelane_b32 v248, s1, 11
	s_cselect_b64 s[0:1], -1, 0
	v_writelane_b32 v248, s0, 12
	s_cmp_eq_u32 s3, 9
	s_nop 0
	v_writelane_b32 v248, s1, 13
	s_cselect_b64 s[0:1], -1, 0
	v_writelane_b32 v248, s0, 14
	s_cmp_eq_u32 s3, 8
	s_nop 0
	v_writelane_b32 v248, s1, 15
	s_cselect_b64 s[0:1], -1, 0
	v_writelane_b32 v248, s0, 16
	s_cmp_eq_u32 s3, 7
	s_nop 0
	v_writelane_b32 v248, s1, 17
	s_cselect_b64 s[0:1], -1, 0
	v_writelane_b32 v248, s0, 18
	s_cmp_eq_u32 s3, 6
	s_nop 0
	v_writelane_b32 v248, s1, 19
	s_cselect_b64 s[0:1], -1, 0
	v_writelane_b32 v248, s0, 20
	s_cmp_eq_u32 s3, 5
	s_nop 0
	v_writelane_b32 v248, s1, 21
	s_cselect_b64 s[0:1], -1, 0
	v_writelane_b32 v248, s0, 22
	s_cmp_eq_u32 s3, 4
	s_nop 0
	v_writelane_b32 v248, s1, 23
	s_cselect_b64 s[0:1], -1, 0
	v_writelane_b32 v248, s0, 24
	s_cmp_eq_u32 s3, 3
	s_nop 0
	v_writelane_b32 v248, s1, 25
	s_cselect_b64 s[0:1], -1, 0
	v_writelane_b32 v248, s0, 26
	s_cmp_eq_u32 s3, 2
	s_nop 0
	v_writelane_b32 v248, s1, 27
	s_cselect_b64 s[0:1], -1, 0
	v_writelane_b32 v248, s0, 28
	s_cmp_eq_u32 s3, 1
	s_nop 0
	v_writelane_b32 v248, s1, 29
	s_cselect_b64 s[0:1], -1, 0
	v_writelane_b32 v248, s0, 30
	s_cmp_eq_u32 s3, 0
	s_nop 0
	v_writelane_b32 v248, s1, 31
	s_cselect_b64 s[0:1], -1, 0
	v_writelane_b32 v248, s0, 32
	s_nop 1
	v_writelane_b32 v248, s1, 33
	s_lshl_b32 s0, s2, 2
	s_add_u32 s0, s4, s0
	s_addc_u32 s1, s5, 0
	s_add_u32 s2, s0, 0x1400
	s_addc_u32 s3, s1, 0
	v_writelane_b32 v248, s2, 34
	s_add_u32 s0, s0, 0x2400
	s_addc_u32 s1, s1, 0
	v_writelane_b32 v248, s3, 35
	v_writelane_b32 v248, s0, 36
	s_mov_b32 s3, 0x20000
	s_mov_b32 s11, s3
	v_writelane_b32 v248, s1, 37
	v_writelane_b32 v248, s8, 38
	s_add_u32 s0, s96, 0xeb14500
	s_addc_u32 s1, s97, 0
	v_writelane_b32 v248, s9, 39
	v_writelane_b32 v248, s10, 40
	v_writelane_b32 v248, s11, 41
	v_writelane_b32 v248, s0, 42
	s_brev_b32 s2, 32
	s_mov_b32 s4, 0x40400000
	v_writelane_b32 v248, s1, 43
	s_add_u32 s0, s96, 0xeb14600
	s_addc_u32 s1, s97, 0
	v_writelane_b32 v248, s0, 44
	s_mov_b32 s8, 0x41300000
	s_mov_b32 s10, 0x41880000
	v_writelane_b32 v248, s1, 45
	v_writelane_b32 v248, s6, 46
	s_lshr_b32 s0, s6, 31
	v_writelane_b32 v248, s0, 47
	s_lshl_b32 s0, s69, 6
	v_writelane_b32 v248, s0, 48
	s_lshl_b32 s0, s98, 6
	v_writelane_b32 v248, s0, 49
	s_add_u32 s0, s96, 0xe68c000
	v_writelane_b32 v248, s0, 50
	s_addc_u32 s0, s97, 0
	v_writelane_b32 v248, s0, 51
	s_add_u32 s0, s96, 0x8080020
	s_addc_u32 s1, s97, 0
	v_writelane_b32 v248, s0, 52
	s_lshl_b32 s82, s98, 1
	s_mov_b32 s6, 0x41100000
	v_writelane_b32 v248, s1, 53
	v_writelane_b32 v248, s0, 54
	s_mov_b32 s5, 0x41000000
	s_mov_b32 s7, 0x41200000
	v_writelane_b32 v248, s1, 55
	v_writelane_b32 v248, s2, 56
	v_writelane_b32 v248, s3, 57
	v_writelane_b32 v248, s16, 58
	s_add_i32 s0, s16, 0xfffeff00
	v_writelane_b32 v248, s0, 59
	s_lshl_b32 s0, s69, 1
	v_writelane_b32 v248, s0, 60
	s_add_i32 s0, 0, 0x240f0
	v_writelane_b32 v248, s0, 61
	s_add_i32 s0, 0, 0x240f4
	v_writelane_b32 v248, s0, 62
	v_writelane_b32 v248, s22, 63
	s_mov_b32 s9, 0x41800000
	s_mov_b32 s11, 0x41900000
	v_writelane_b32 v243, s23, 0
	v_writelane_b32 v243, s84, 1
	s_mov_b32 s3, 0xff800000
	s_add_i32 s33, 0, 0x12000
	v_writelane_b32 v243, s85, 2
	v_writelane_b32 v243, s28, 3
	s_mov_b32 s0, 0
	s_nop 0
	v_writelane_b32 v243, s29, 4
	v_writelane_b32 v243, s34, 5
	s_nop 1
	v_writelane_b32 v243, s35, 6
	v_writelane_b32 v243, s86, 7
	v_writelane_b32 v243, s87, 8
	v_writelane_b32 v243, s83, 9
	v_writelane_b32 v243, s68, 10
	v_writelane_b32 v243, s80, 11
	v_writelane_b32 v243, s90, 12
	v_writelane_b32 v243, s91, 13
	v_writelane_b32 v243, s81, 14
	v_writelane_b32 v243, s82, 15
	v_writelane_b32 v243, s69, 16
	v_writelane_b32 v243, s70, 17
	s_nop 1
	v_writelane_b32 v243, s71, 18
	v_writelane_b32 v243, 0, 60
	v_writelane_b32 v243, 0, 62
	v_writelane_b32 v243, 0, 61
	s_branch .LBB0_9

.LBB0_156:
	s_andn2_b64 vcc, exec, s[22:23]
	s_cbranch_vccnz .LBB0_228
	s_waitcnt lgkmcnt(0)
	v_bfe_i32 v3, v14, 27, 1
	v_lshlrev_b32_e32 v1, 4, v14
	v_lshrrev_b32_e32 v3, 22, v3
	v_add_u32_e32 v3, v1, v3
	v_and_b32_e32 v3, 0xfffffc00, v3
	v_ashrrev_i32_e32 v2, 31, v14
	v_sub_u32_e32 v3, v1, v3
	v_lshrrev_b32_e32 v2, 26, v2
	v_lshrrev_b32_e32 v4, 4, v3
	v_add_u32_e32 v2, v14, v2
	v_bitop3_b32 v4, v4, v3, 32 bitop3:0x6c
	v_ashrrev_i32_e32 v3, 31, v3
	v_ashrrev_i32_e32 v2, 6, v2
	v_lshrrev_b32_e32 v3, 26, v3
	v_lshlrev_b32_e32 v5, 3, v2
	v_add_u32_e32 v3, v4, v3
	v_and_b32_e32 v5, -16, v5
	v_ashrrev_i32_e32 v3, 6, v3
	v_lshlrev_b32_e32 v2, 5, v2
	v_add_u32_e32 v5, v3, v5
	v_and_b32_e32 v15, 32, v2
	v_mul_i32_i24_e32 v2, 64, v3
	v_sub_u32_e32 v2, v4, v2
	v_lshlrev_b32_e32 v4, 1, v5
	v_lshrrev_b32_e32 v6, 2, v5
	v_and_b32_e32 v3, 3, v3
	s_mov_b32 s2, 0x7fffffe0
	v_ashrrev_i16_sdwa v2, v222, sext(v2) dst_sel:DWORD dst_unused:UNUSED_PAD src0_sel:DWORD src1_sel:BYTE_0
	v_and_b32_e32 v4, 24, v4
	v_and_b32_e32 v6, 4, v6
	v_and_or_b32 v3, v5, s2, v3
	v_bfe_i32 v16, v2, 0, 16
	v_or3_b32 v3, v3, v6, v4
	v_add_u32_e32 v2, v15, v16
	v_mul_lo_u32 v17, v5, s39
	v_mul_lo_u32 v3, v3, s38
	v_add_u32_e32 v1, 0x2000, v1
	v_add_lshl_u32 v186, v2, v17, 1
	v_add_lshl_u32 v188, v3, v2, 1
	v_ashrrev_i32_e32 v2, 31, v1
	v_lshrrev_b32_e32 v2, 22, v2
	v_add_u32_e32 v2, v1, v2
	v_ashrrev_i32_e32 v2, 10, v2
	v_mul_i32_i24_e32 v3, 0x400, v2
	v_sub_u32_e32 v1, v1, v3
	v_lshrrev_b32_e32 v3, 4, v1
	v_bitop3_b32 v1, v3, v1, 32 bitop3:0x6c
	v_ashrrev_i32_e32 v4, 31, v1
	s_lshl_b32 s16, s39, 8
	v_lshrrev_b32_e32 v4, 26, v4
	s_lshl_b64 s[62:63], s[16:17], 1
	s_ashr_i32 s21, s99, 31
	v_writelane_b32 v243, s59, 32
	v_lshlrev_b32_e32 v3, 3, v2
	v_add_u32_e32 v4, v1, v4
	s_mul_i32 s21, s62, s21
	s_mul_hi_u32 s22, s62, s99
	v_writelane_b32 v243, s56, 42
	v_and_b32_e32 v3, -16, v3
	v_ashrrev_i32_e32 v5, 6, v4
	s_add_i32 s21, s22, s21
	s_bfe_u32 s22, s39, 0x10017
	v_writelane_b32 v243, s57, 43
	s_ashr_i32 s1, s0, 6
	v_add_u32_e32 v3, v5, v3
	v_lshlrev_b32_e32 v2, 5, v2
	v_and_b32_e32 v5, 3, v5
	s_lshl_b32 s56, s38, 9
	s_mul_i32 s22, s22, s99
	v_and_b32_e32 v18, 32, v2
	v_and_b32_e32 v2, 0xc0, v4
	v_and_or_b32 v5, v3, s2, v5
	s_ashr_i32 s2, s0, 8
	s_lshl_b32 s69, s38, 8
	s_lshl_b32 s57, s1, 10
	s_add_i32 s21, s21, s22
	s_mul_i32 s23, s56, s88
	v_sub_u32_e32 v1, v1, v2
	v_lshlrev_b32_e32 v2, 1, v3
	v_lshrrev_b32_e32 v4, 2, v3
	s_mul_hi_i32 s22, s56, s88
	s_add_u32 s34, s48, s23
	v_ashrrev_i16_sdwa v1, v222, sext(v1) dst_sel:DWORD dst_unused:UNUSED_PAD src0_sel:DWORD src1_sel:BYTE_0
	v_and_b32_e32 v2, 24, v2
	v_and_b32_e32 v4, 4, v4
	s_addc_u32 s35, s49, s22
	s_add_i32 s90, s57, 0
	v_bfe_i32 v19, v1, 0, 16
	v_or3_b32 v2, v5, v4, v2
	s_add_i32 m0, s90, 0x10000
	v_add_u32_e32 v1, v18, v19
	v_mul_lo_u32 v2, v2, s38
	global_load_lds_dwordx4 v188, s[34:35]
	s_add_i32 m0, s90, 0x12000
	v_add_lshl_u32 v192, v2, v1, 1
	s_add_u32 s22, s34, s69
	global_load_lds_dwordx4 v192, s[34:35]
	s_addc_u32 s23, s35, 0
	s_add_i32 m0, s90, 0x14000
	v_mul_lo_u32 v20, v3, s39
	s_mul_i32 s39, s62, s99
	global_load_lds_dwordx4 v188, s[22:23]
	s_add_i32 m0, s90, 0x16000
	s_add_u32 s80, s54, s39
	v_mov_b32_e32 v189, v0
	v_mov_b32_e32 v193, v0
	s_addc_u32 s81, s55, s21
	s_add_i32 s60, s90, 0x2000
	v_lshl_add_u64 v[6:7], s[22:23], 0, v[188:189]
	v_lshl_add_u64 v[8:9], s[22:23], 0, v[192:193]
	global_load_lds_dwordx4 v192, s[22:23]
	v_readlane_b32 vcc_lo, v243, 62
	s_cmp_eq_u32 vcc_lo, 0
	s_cbranch_scc1 .Ltd_done
	s_nop 0
	v_writelane_b32 v243, 0, 62
	v_readlane_b32 s22, v243, 16
	s_and_b32 s22, s22, 63
	s_lshl_b32 s22, s22, 5
	s_add_u32 vcc_hi, s96, 0xeb12d00
	s_addc_u32 s23, s97, 0
	s_add_u32 s22, vcc_hi, s22
	s_addc_u32 s23, s23, 0
	v_readlane_b32 vcc_lo, v243, 60
	s_lshl_b32 vcc_lo, vcc_lo, 2
.Ltd_poll:
	global_load_dword v240, v0, s[22:23] sc1
	s_waitcnt vmcnt(0)
	v_readfirstlane_b32 vcc_hi, v240
	s_cmp_ge_u32 vcc_hi, vcc_lo
	s_cbranch_scc1 .Ltd_done
	s_sleep 1
	s_branch .Ltd_poll
.Ltd_done:
	s_mov_b32 m0, s90
	s_add_u32 s22, s80, s16
	v_add_lshl_u32 v190, v1, v20, 1
	global_load_lds_dwordx4 v186, s[80:81]
	s_mov_b32 m0, s60
	s_addc_u32 s23, s81, 0
	s_add_i32 s61, s90, 0x4000
	global_load_lds_dwordx4 v190, s[80:81]
	s_mov_b32 m0, s61
	s_add_i32 s71, s90, 0x6000
	global_load_lds_dwordx4 v186, s[22:23]
	s_mov_b32 m0, s71
	v_writelane_b32 v243, s47, 40
	global_load_lds_dwordx4 v190, s[22:23]
	v_writelane_b32 v243, s52, 44
	s_cmp_eq_u32 s2, 1
	v_mov_b32_e32 v187, v0
	v_writelane_b32 v243, s53, 45
	v_mov_b32_e32 v191, v0
	s_cselect_b64 s[22:23], -1, 0
	v_lshl_add_u64 v[2:3], s[34:35], 0, v[188:189]
	v_lshl_add_u64 v[4:5], s[34:35], 0, v[192:193]
	v_lshl_add_u64 v[10:11], s[80:81], 0, v[186:187]
	v_lshl_add_u64 v[12:13], s[80:81], 0, v[190:191]
	v_writelane_b32 v243, s22, 30
	s_cmp_lg_u32 s2, 1
	s_nop 0
	v_writelane_b32 v243, s23, 31
	s_cbranch_scc1 .LBB0_159
	s_barrier

.Lp0s_skip:
	v_readlane_b32 s82, v243, 15
	v_readlane_b32 s83, v243, 9
	v_readlane_b32 s69, v243, 16
	v_readlane_b32 s0, v243, 19
	v_readlane_b32 s22, v243, 20
	s_cmp_lg_u32 s0, 20
	s_mul_hi_u32 s16, s22, 0xcccccccd
	s_cselect_b64 s[0:1], -1, 0
	s_lshr_b32 s16, s16, 3
	s_mul_i32 s16, s16, 10
	s_sub_i32 s16, s22, s16
	s_cmp_lg_u32 s16, 6
	s_cselect_b64 s[22:23], -1, 0
	s_and_b64 s[0:1], s[0:1], s[22:23]
	s_andn2_b64 vcc, exec, s[0:1]
	s_cbranch_vccnz .LBB0_8
	s_waitcnt vmcnt(0)
	s_waitcnt vmcnt(0) lgkmcnt(0)
	s_barrier
	s_cmpk_lg_u32 s98, 0x100
	s_cbranch_scc1 .Ltb_cnt_done
	v_readlane_b32 s0, v243, 19
	s_mov_b32 s1, 0xc9f24
	s_lshr_b32 s1, s1, s0
	s_and_b32 s1, s1, 1
	s_cmp_eq_u32 s1, 0
	s_cbranch_scc1 .Ltb_cnt_done
	v_readlane_b32 s0, v243, 60
	s_add_i32 s0, s0, 1
	s_nop 0
	v_writelane_b32 v243, s0, 60
	v_writelane_b32 v243, 1, 62
.Ltb_cnt_done:
	s_and_saveexec_b64 s[22:23], s[84:85]
	s_cbranch_execz .LBB0_7
	s_cmpk_lg_u32 s98, 0x100
	s_cbranch_scc1 .Ltb_full
	v_readlane_b32 s0, v243, 19
	s_mov_b32 s1, 0xc9f24
	s_lshr_b32 s1, s1, s0
	s_and_b32 s1, s1, 1
	s_cmp_eq_u32 s1, 0
	s_cbranch_scc1 .Ltb_full
	v_readlane_b32 s0, v243, 16
	s_and_b32 s0, s0, 63
	s_lshl_b32 s0, s0, 5
	s_add_u32 s28, s96, 0xeb12d00
	s_addc_u32 s29, s97, 0
	s_add_u32 s28, s28, s0
	s_addc_u32 s29, s29, 0
	v_mov_b32_e32 v1, 1
	global_atomic_add v0, v1, s[28:29]
	buffer_inv sc1
	s_branch .LBB0_7
